# O2 threshold-search counting via v_med3_u32 + v_add3_u32 (no SGPR masks), rest as v6
# baseline (speedup 1.0000x reference)
; __global__ void __launch_bounds__(512, 2) mega_fwd(KArgs a) {
;     ...
; #pragma unroll 1
;     ...
;                     const unsigned cand = tau | (1u << bit);
;                     int c0 = 0, c1 = 0;
; #pragma unroll
;                     for (int jj = 0; jj < 64; ++jj) { const unsigned long long bm = __ballot(key[jj] >= cand); c0 += __popc((unsigned)bm); c1 += __popc((unsigned)(bm >> 32)); }
;                     const int cnt = (lane < 32) ? c0 : c1;
;                     if (cnt >= 256) tau = cand;
;                     done_sel = done_sel || (cnt == 256);
;                     if (__ballot(!done_sel) == 0ull) break;
;                 }
.Lmy_sel_loop_8:
	v_lshl_or_b32 v12, 1, v11, v10
	v_add_u32_e32 v14, -1, v12
	v_mov_b32_e32 v13, 0
	v_med3_u32 v15, v3, v12, v14
	v_med3_u32 v16, v2, v12, v14
	v_add3_u32 v13, v13, v15, v16
	v_med3_u32 v15, v5, v12, v14
	v_med3_u32 v16, v4, v12, v14
	v_add3_u32 v13, v13, v15, v16
	v_med3_u32 v15, v7, v12, v14
	v_med3_u32 v16, v6, v12, v14
	v_add3_u32 v13, v13, v15, v16
	v_med3_u32 v15, v9, v12, v14
	v_med3_u32 v16, v8, v12, v14
	v_add3_u32 v13, v13, v15, v16
	v_med3_u32 v15, v102, v12, v14
	v_med3_u32 v16, v97, v12, v14
	v_add3_u32 v13, v13, v15, v16
	v_med3_u32 v15, v104, v12, v14
	v_med3_u32 v16, v99, v12, v14
	v_add3_u32 v13, v13, v15, v16
	v_med3_u32 v15, v106, v12, v14
	v_med3_u32 v16, v101, v12, v14
	v_add3_u32 v13, v13, v15, v16
	v_med3_u32 v15, v108, v12, v14
	v_med3_u32 v16, v103, v12, v14
	v_add3_u32 v13, v13, v15, v16
	v_med3_u32 v15, v110, v12, v14
	v_med3_u32 v16, v105, v12, v14
	v_add3_u32 v13, v13, v15, v16
	v_med3_u32 v15, v112, v12, v14
	v_med3_u32 v16, v107, v12, v14
	v_add3_u32 v13, v13, v15, v16
	v_med3_u32 v15, v114, v12, v14
	v_med3_u32 v16, v109, v12, v14
	v_add3_u32 v13, v13, v15, v16
	v_med3_u32 v15, v116, v12, v14
	v_med3_u32 v16, v111, v12, v14
	v_add3_u32 v13, v13, v15, v16
	v_med3_u32 v15, v118, v12, v14
	v_med3_u32 v16, v113, v12, v14
	v_add3_u32 v13, v13, v15, v16
	v_med3_u32 v15, v120, v12, v14
	v_med3_u32 v16, v115, v12, v14
	v_add3_u32 v13, v13, v15, v16
	v_med3_u32 v15, v122, v12, v14
	v_med3_u32 v16, v117, v12, v14
	v_add3_u32 v13, v13, v15, v16
	v_med3_u32 v15, v124, v12, v14
	v_med3_u32 v16, v119, v12, v14
	v_add3_u32 v13, v13, v15, v16
	v_med3_u32 v15, v158, v12, v14
	v_med3_u32 v16, v121, v12, v14
	v_add3_u32 v13, v13, v15, v16
	v_med3_u32 v15, v160, v12, v14
	v_med3_u32 v16, v123, v12, v14
	v_add3_u32 v13, v13, v15, v16
	v_med3_u32 v15, v162, v12, v14
	v_med3_u32 v16, v125, v12, v14
	v_add3_u32 v13, v13, v15, v16
	v_med3_u32 v15, v164, v12, v14
	v_med3_u32 v16, v159, v12, v14
	v_add3_u32 v13, v13, v15, v16
	v_med3_u32 v15, v168, v12, v14
	v_med3_u32 v16, v161, v12, v14
	v_add3_u32 v13, v13, v15, v16
	v_med3_u32 v15, v170, v12, v14
	v_med3_u32 v16, v163, v12, v14
	v_add3_u32 v13, v13, v15, v16
	v_med3_u32 v15, v172, v12, v14
	v_med3_u32 v16, v165, v12, v14
	v_add3_u32 v13, v13, v15, v16
	v_med3_u32 v15, v174, v12, v14
	v_med3_u32 v16, v169, v12, v14
	v_add3_u32 v13, v13, v15, v16
	v_med3_u32 v15, v176, v12, v14
	v_med3_u32 v16, v171, v12, v14
	v_add3_u32 v13, v13, v15, v16
	v_med3_u32 v15, v178, v12, v14
	v_med3_u32 v16, v173, v12, v14
	v_add3_u32 v13, v13, v15, v16
	v_med3_u32 v15, v180, v12, v14
	v_med3_u32 v16, v175, v12, v14
	v_add3_u32 v13, v13, v15, v16
	v_med3_u32 v15, v182, v12, v14
	v_med3_u32 v16, v177, v12, v14
	v_add3_u32 v13, v13, v15, v16
	v_med3_u32 v15, v184, v12, v14
	v_med3_u32 v16, v179, v12, v14
	v_add3_u32 v13, v13, v15, v16
	v_med3_u32 v15, v186, v12, v14
	v_med3_u32 v16, v181, v12, v14
	v_add3_u32 v13, v13, v15, v16
	v_med3_u32 v15, v188, v12, v14
	v_med3_u32 v16, v183, v12, v14
	v_add3_u32 v13, v13, v15, v16
	v_med3_u32 v15, v190, v12, v14
	v_med3_u32 v16, v185, v12, v14
	v_add3_u32 v13, v13, v15, v16
	v_mul_lo_u32 v15, v14, 64
	v_sub_u32_e32 v13, v13, v15
	s_nop 1
	v_add_u32_dpp v13, v13, v13 quad_perm:[1,0,3,2] row_mask:0xf bank_mask:0xf
	s_nop 1
	v_add_u32_dpp v13, v13, v13 quad_perm:[2,3,0,1] row_mask:0xf bank_mask:0xf
	s_nop 1
	v_add_u32_dpp v13, v13, v13 row_half_mirror row_mask:0xf bank_mask:0xf
	s_nop 1
	v_add_u32_dpp v13, v13, v13 row_mirror row_mask:0xf bank_mask:0xf
	v_mov_b32_e32 v14, v13
	s_nop 1
	v_permlane16_swap_b32 v14, v13
	v_add_u32_e32 v13, v13, v14
	s_movk_i32 s2, 0xff
	v_cmp_lt_i32_e32 vcc, s2, v13
	s_nop 1
	v_cndmask_b32_e32 v10, v10, v12, vcc
	v_cmp_eq_u32_e32 vcc, s5, v13
	s_or_b64 s[0:1], s[0:1], vcc
	s_xor_b64 s[2:3], s[0:1], -1
	v_cndmask_b32_e64 v12, 0, 1, s[2:3]
	v_cmp_ne_u32_e32 vcc, 0, v12
	s_cmp_lg_u64 vcc, 0
	s_cselect_b64 s[2:3], -1, 0
	v_add_co_u32_e32 v11, vcc, -1, v11
	s_and_b64 s[2:3], s[2:3], vcc
	s_and_b64 vcc, exec, s[2:3]
	s_cbranch_vccnz .Lmy_sel_loop_8
	s_andn2_b64 s[2:3], exec, s[0:1]
	s_cbranch_scc0 .Lmy_sel_fast_8
	s_branch .Lmy_sel_slow

; __global__ void __launch_bounds__(512, 2) mega_fwd(KArgs a) {
;     ...
; #pragma unroll 1
;     ...
;                     const unsigned cand = tau | (1u << bit);
;                     int c0 = 0, c1 = 0;
; #pragma unroll
;                     for (int jj = 0; jj < 64; ++jj) { const unsigned long long bm = __ballot(key[jj] >= cand); c0 += __popc((unsigned)bm); c1 += __popc((unsigned)(bm >> 32)); }
;                     const int cnt = (lane < 32) ? c0 : c1;
;                     if (cnt >= 256) tau = cand;
;                     done_sel = done_sel || (cnt == 256);
;                     if (__ballot(!done_sel) == 0ull) break;
;                 }
.Lmy_sel_loop_7:
	v_lshl_or_b32 v12, 1, v11, v10
	v_add_u32_e32 v14, -1, v12
	v_mov_b32_e32 v13, 0
	v_med3_u32 v15, v3, v12, v14
	v_med3_u32 v16, v2, v12, v14
	v_add3_u32 v13, v13, v15, v16
	v_med3_u32 v15, v5, v12, v14
	v_med3_u32 v16, v4, v12, v14
	v_add3_u32 v13, v13, v15, v16
	v_med3_u32 v15, v7, v12, v14
	v_med3_u32 v16, v6, v12, v14
	v_add3_u32 v13, v13, v15, v16
	v_med3_u32 v15, v9, v12, v14
	v_med3_u32 v16, v8, v12, v14
	v_add3_u32 v13, v13, v15, v16
	v_med3_u32 v15, v102, v12, v14
	v_med3_u32 v16, v97, v12, v14
	v_add3_u32 v13, v13, v15, v16
	v_med3_u32 v15, v104, v12, v14
	v_med3_u32 v16, v99, v12, v14
	v_add3_u32 v13, v13, v15, v16
	v_med3_u32 v15, v106, v12, v14
	v_med3_u32 v16, v101, v12, v14
	v_add3_u32 v13, v13, v15, v16
	v_med3_u32 v15, v108, v12, v14
	v_med3_u32 v16, v103, v12, v14
	v_add3_u32 v13, v13, v15, v16
	v_med3_u32 v15, v110, v12, v14
	v_med3_u32 v16, v105, v12, v14
	v_add3_u32 v13, v13, v15, v16
	v_med3_u32 v15, v112, v12, v14
	v_med3_u32 v16, v107, v12, v14
	v_add3_u32 v13, v13, v15, v16
	v_med3_u32 v15, v114, v12, v14
	v_med3_u32 v16, v109, v12, v14
	v_add3_u32 v13, v13, v15, v16
	v_med3_u32 v15, v116, v12, v14
	v_med3_u32 v16, v111, v12, v14
	v_add3_u32 v13, v13, v15, v16
	v_med3_u32 v15, v118, v12, v14
	v_med3_u32 v16, v113, v12, v14
	v_add3_u32 v13, v13, v15, v16
	v_med3_u32 v15, v120, v12, v14
	v_med3_u32 v16, v115, v12, v14
	v_add3_u32 v13, v13, v15, v16
	v_med3_u32 v15, v122, v12, v14
	v_med3_u32 v16, v117, v12, v14
	v_add3_u32 v13, v13, v15, v16
	v_med3_u32 v15, v124, v12, v14
	v_med3_u32 v16, v119, v12, v14
	v_add3_u32 v13, v13, v15, v16
	v_med3_u32 v15, v158, v12, v14
	v_med3_u32 v16, v121, v12, v14
	v_add3_u32 v13, v13, v15, v16
	v_med3_u32 v15, v160, v12, v14
	v_med3_u32 v16, v123, v12, v14
	v_add3_u32 v13, v13, v15, v16
	v_med3_u32 v15, v162, v12, v14
	v_med3_u32 v16, v125, v12, v14
	v_add3_u32 v13, v13, v15, v16
	v_med3_u32 v15, v164, v12, v14
	v_med3_u32 v16, v159, v12, v14
	v_add3_u32 v13, v13, v15, v16
	v_med3_u32 v15, v168, v12, v14
	v_med3_u32 v16, v161, v12, v14
	v_add3_u32 v13, v13, v15, v16
	v_med3_u32 v15, v170, v12, v14
	v_med3_u32 v16, v163, v12, v14
	v_add3_u32 v13, v13, v15, v16
	v_med3_u32 v15, v172, v12, v14
	v_med3_u32 v16, v165, v12, v14
	v_add3_u32 v13, v13, v15, v16
	v_med3_u32 v15, v174, v12, v14
	v_med3_u32 v16, v169, v12, v14
	v_add3_u32 v13, v13, v15, v16
	v_med3_u32 v15, v176, v12, v14
	v_med3_u32 v16, v171, v12, v14
	v_add3_u32 v13, v13, v15, v16
	v_med3_u32 v15, v178, v12, v14
	v_med3_u32 v16, v173, v12, v14
	v_add3_u32 v13, v13, v15, v16
	v_med3_u32 v15, v180, v12, v14
	v_med3_u32 v16, v175, v12, v14
	v_add3_u32 v13, v13, v15, v16
	v_med3_u32 v15, v182, v12, v14
	v_med3_u32 v16, v177, v12, v14
	v_add3_u32 v13, v13, v15, v16
	v_mul_lo_u32 v15, v14, 56
	v_sub_u32_e32 v13, v13, v15
	s_nop 1
	v_add_u32_dpp v13, v13, v13 quad_perm:[1,0,3,2] row_mask:0xf bank_mask:0xf
	s_nop 1
	v_add_u32_dpp v13, v13, v13 quad_perm:[2,3,0,1] row_mask:0xf bank_mask:0xf
	s_nop 1
	v_add_u32_dpp v13, v13, v13 row_half_mirror row_mask:0xf bank_mask:0xf
	s_nop 1
	v_add_u32_dpp v13, v13, v13 row_mirror row_mask:0xf bank_mask:0xf
	v_mov_b32_e32 v14, v13
	s_nop 1
	v_permlane16_swap_b32 v14, v13
	v_add_u32_e32 v13, v13, v14
	s_movk_i32 s2, 0xff
	v_cmp_lt_i32_e32 vcc, s2, v13
	s_nop 1
	v_cndmask_b32_e32 v10, v10, v12, vcc
	v_cmp_eq_u32_e32 vcc, s5, v13
	s_or_b64 s[0:1], s[0:1], vcc
	s_xor_b64 s[2:3], s[0:1], -1
	v_cndmask_b32_e64 v12, 0, 1, s[2:3]
	v_cmp_ne_u32_e32 vcc, 0, v12
	s_cmp_lg_u64 vcc, 0
	s_cselect_b64 s[2:3], -1, 0
	v_add_co_u32_e32 v11, vcc, -1, v11
	s_and_b64 s[2:3], s[2:3], vcc
	s_and_b64 vcc, exec, s[2:3]
	s_cbranch_vccnz .Lmy_sel_loop_7
	s_andn2_b64 s[2:3], exec, s[0:1]
	s_cbranch_scc0 .Lmy_sel_fast_7
	s_branch .Lmy_sel_slow

; __global__ void __launch_bounds__(512, 2) mega_fwd(KArgs a) {
;     ...
; #pragma unroll 1
;     ...
;                     const unsigned cand = tau | (1u << bit);
;                     int c0 = 0, c1 = 0;
; #pragma unroll
;                     for (int jj = 0; jj < 64; ++jj) { const unsigned long long bm = __ballot(key[jj] >= cand); c0 += __popc((unsigned)bm); c1 += __popc((unsigned)(bm >> 32)); }
;                     const int cnt = (lane < 32) ? c0 : c1;
;                     if (cnt >= 256) tau = cand;
;                     done_sel = done_sel || (cnt == 256);
;                     if (__ballot(!done_sel) == 0ull) break;
;                 }
.Lmy_sel_loop_6:
	v_lshl_or_b32 v12, 1, v11, v10
	v_add_u32_e32 v14, -1, v12
	v_mov_b32_e32 v13, 0
	v_med3_u32 v15, v3, v12, v14
	v_med3_u32 v16, v2, v12, v14
	v_add3_u32 v13, v13, v15, v16
	v_med3_u32 v15, v5, v12, v14
	v_med3_u32 v16, v4, v12, v14
	v_add3_u32 v13, v13, v15, v16
	v_med3_u32 v15, v7, v12, v14
	v_med3_u32 v16, v6, v12, v14
	v_add3_u32 v13, v13, v15, v16
	v_med3_u32 v15, v9, v12, v14
	v_med3_u32 v16, v8, v12, v14
	v_add3_u32 v13, v13, v15, v16
	v_med3_u32 v15, v102, v12, v14
	v_med3_u32 v16, v97, v12, v14
	v_add3_u32 v13, v13, v15, v16
	v_med3_u32 v15, v104, v12, v14
	v_med3_u32 v16, v99, v12, v14
	v_add3_u32 v13, v13, v15, v16
	v_med3_u32 v15, v106, v12, v14
	v_med3_u32 v16, v101, v12, v14
	v_add3_u32 v13, v13, v15, v16
	v_med3_u32 v15, v108, v12, v14
	v_med3_u32 v16, v103, v12, v14
	v_add3_u32 v13, v13, v15, v16
	v_med3_u32 v15, v110, v12, v14
	v_med3_u32 v16, v105, v12, v14
	v_add3_u32 v13, v13, v15, v16
	v_med3_u32 v15, v112, v12, v14
	v_med3_u32 v16, v107, v12, v14
	v_add3_u32 v13, v13, v15, v16
	v_med3_u32 v15, v114, v12, v14
	v_med3_u32 v16, v109, v12, v14
	v_add3_u32 v13, v13, v15, v16
	v_med3_u32 v15, v116, v12, v14
	v_med3_u32 v16, v111, v12, v14
	v_add3_u32 v13, v13, v15, v16
	v_med3_u32 v15, v118, v12, v14
	v_med3_u32 v16, v113, v12, v14
	v_add3_u32 v13, v13, v15, v16
	v_med3_u32 v15, v120, v12, v14
	v_med3_u32 v16, v115, v12, v14
	v_add3_u32 v13, v13, v15, v16
	v_med3_u32 v15, v122, v12, v14
	v_med3_u32 v16, v117, v12, v14
	v_add3_u32 v13, v13, v15, v16
	v_med3_u32 v15, v124, v12, v14
	v_med3_u32 v16, v119, v12, v14
	v_add3_u32 v13, v13, v15, v16
	v_med3_u32 v15, v158, v12, v14
	v_med3_u32 v16, v121, v12, v14
	v_add3_u32 v13, v13, v15, v16
	v_med3_u32 v15, v160, v12, v14
	v_med3_u32 v16, v123, v12, v14
	v_add3_u32 v13, v13, v15, v16
	v_med3_u32 v15, v162, v12, v14
	v_med3_u32 v16, v125, v12, v14
	v_add3_u32 v13, v13, v15, v16
	v_med3_u32 v15, v164, v12, v14
	v_med3_u32 v16, v159, v12, v14
	v_add3_u32 v13, v13, v15, v16
	v_med3_u32 v15, v168, v12, v14
	v_med3_u32 v16, v161, v12, v14
	v_add3_u32 v13, v13, v15, v16
	v_med3_u32 v15, v170, v12, v14
	v_med3_u32 v16, v163, v12, v14
	v_add3_u32 v13, v13, v15, v16
	v_med3_u32 v15, v172, v12, v14
	v_med3_u32 v16, v165, v12, v14
	v_add3_u32 v13, v13, v15, v16
	v_med3_u32 v15, v174, v12, v14
	v_med3_u32 v16, v169, v12, v14
	v_add3_u32 v13, v13, v15, v16
	v_mul_lo_u32 v15, v14, 48
	v_sub_u32_e32 v13, v13, v15
	s_nop 1
	v_add_u32_dpp v13, v13, v13 quad_perm:[1,0,3,2] row_mask:0xf bank_mask:0xf
	s_nop 1
	v_add_u32_dpp v13, v13, v13 quad_perm:[2,3,0,1] row_mask:0xf bank_mask:0xf
	s_nop 1
	v_add_u32_dpp v13, v13, v13 row_half_mirror row_mask:0xf bank_mask:0xf
	s_nop 1
	v_add_u32_dpp v13, v13, v13 row_mirror row_mask:0xf bank_mask:0xf
	v_mov_b32_e32 v14, v13
	s_nop 1
	v_permlane16_swap_b32 v14, v13
	v_add_u32_e32 v13, v13, v14
	s_movk_i32 s2, 0xff
	v_cmp_lt_i32_e32 vcc, s2, v13
	s_nop 1
	v_cndmask_b32_e32 v10, v10, v12, vcc
	v_cmp_eq_u32_e32 vcc, s5, v13
	s_or_b64 s[0:1], s[0:1], vcc
	s_xor_b64 s[2:3], s[0:1], -1
	v_cndmask_b32_e64 v12, 0, 1, s[2:3]
	v_cmp_ne_u32_e32 vcc, 0, v12
	s_cmp_lg_u64 vcc, 0
	s_cselect_b64 s[2:3], -1, 0
	v_add_co_u32_e32 v11, vcc, -1, v11
	s_and_b64 s[2:3], s[2:3], vcc
	s_and_b64 vcc, exec, s[2:3]
	s_cbranch_vccnz .Lmy_sel_loop_6
	s_andn2_b64 s[2:3], exec, s[0:1]
	s_cbranch_scc0 .Lmy_sel_fast_6
	s_branch .Lmy_sel_slow

; __global__ void __launch_bounds__(512, 2) mega_fwd(KArgs a) {
;     ...
; #pragma unroll 1
;     ...
;                     const unsigned cand = tau | (1u << bit);
;                     int c0 = 0, c1 = 0;
; #pragma unroll
;                     for (int jj = 0; jj < 64; ++jj) { const unsigned long long bm = __ballot(key[jj] >= cand); c0 += __popc((unsigned)bm); c1 += __popc((unsigned)(bm >> 32)); }
;                     const int cnt = (lane < 32) ? c0 : c1;
;                     if (cnt >= 256) tau = cand;
;                     done_sel = done_sel || (cnt == 256);
;                     if (__ballot(!done_sel) == 0ull) break;
;                 }
.Lmy_sel_loop_5:
	v_lshl_or_b32 v12, 1, v11, v10
	v_add_u32_e32 v14, -1, v12
	v_mov_b32_e32 v13, 0
	v_med3_u32 v15, v3, v12, v14
	v_med3_u32 v16, v2, v12, v14
	v_add3_u32 v13, v13, v15, v16
	v_med3_u32 v15, v5, v12, v14
	v_med3_u32 v16, v4, v12, v14
	v_add3_u32 v13, v13, v15, v16
	v_med3_u32 v15, v7, v12, v14
	v_med3_u32 v16, v6, v12, v14
	v_add3_u32 v13, v13, v15, v16
	v_med3_u32 v15, v9, v12, v14
	v_med3_u32 v16, v8, v12, v14
	v_add3_u32 v13, v13, v15, v16
	v_med3_u32 v15, v102, v12, v14
	v_med3_u32 v16, v97, v12, v14
	v_add3_u32 v13, v13, v15, v16
	v_med3_u32 v15, v104, v12, v14
	v_med3_u32 v16, v99, v12, v14
	v_add3_u32 v13, v13, v15, v16
	v_med3_u32 v15, v106, v12, v14
	v_med3_u32 v16, v101, v12, v14
	v_add3_u32 v13, v13, v15, v16
	v_med3_u32 v15, v108, v12, v14
	v_med3_u32 v16, v103, v12, v14
	v_add3_u32 v13, v13, v15, v16
	v_med3_u32 v15, v110, v12, v14
	v_med3_u32 v16, v105, v12, v14
	v_add3_u32 v13, v13, v15, v16
	v_med3_u32 v15, v112, v12, v14
	v_med3_u32 v16, v107, v12, v14
	v_add3_u32 v13, v13, v15, v16
	v_med3_u32 v15, v114, v12, v14
	v_med3_u32 v16, v109, v12, v14
	v_add3_u32 v13, v13, v15, v16
	v_med3_u32 v15, v116, v12, v14
	v_med3_u32 v16, v111, v12, v14
	v_add3_u32 v13, v13, v15, v16
	v_med3_u32 v15, v118, v12, v14
	v_med3_u32 v16, v113, v12, v14
	v_add3_u32 v13, v13, v15, v16
	v_med3_u32 v15, v120, v12, v14
	v_med3_u32 v16, v115, v12, v14
	v_add3_u32 v13, v13, v15, v16
	v_med3_u32 v15, v122, v12, v14
	v_med3_u32 v16, v117, v12, v14
	v_add3_u32 v13, v13, v15, v16
	v_med3_u32 v15, v124, v12, v14
	v_med3_u32 v16, v119, v12, v14
	v_add3_u32 v13, v13, v15, v16
	v_med3_u32 v15, v158, v12, v14
	v_med3_u32 v16, v121, v12, v14
	v_add3_u32 v13, v13, v15, v16
	v_med3_u32 v15, v160, v12, v14
	v_med3_u32 v16, v123, v12, v14
	v_add3_u32 v13, v13, v15, v16
	v_med3_u32 v15, v162, v12, v14
	v_med3_u32 v16, v125, v12, v14
	v_add3_u32 v13, v13, v15, v16
	v_med3_u32 v15, v164, v12, v14
	v_med3_u32 v16, v159, v12, v14
	v_add3_u32 v13, v13, v15, v16
	v_mul_lo_u32 v15, v14, 40
	v_sub_u32_e32 v13, v13, v15
	s_nop 1
	v_add_u32_dpp v13, v13, v13 quad_perm:[1,0,3,2] row_mask:0xf bank_mask:0xf
	s_nop 1
	v_add_u32_dpp v13, v13, v13 quad_perm:[2,3,0,1] row_mask:0xf bank_mask:0xf
	s_nop 1
	v_add_u32_dpp v13, v13, v13 row_half_mirror row_mask:0xf bank_mask:0xf
	s_nop 1
	v_add_u32_dpp v13, v13, v13 row_mirror row_mask:0xf bank_mask:0xf
	v_mov_b32_e32 v14, v13
	s_nop 1
	v_permlane16_swap_b32 v14, v13
	v_add_u32_e32 v13, v13, v14
	s_movk_i32 s2, 0xff
	v_cmp_lt_i32_e32 vcc, s2, v13
	s_nop 1
	v_cndmask_b32_e32 v10, v10, v12, vcc
	v_cmp_eq_u32_e32 vcc, s5, v13
	s_or_b64 s[0:1], s[0:1], vcc
	s_xor_b64 s[2:3], s[0:1], -1
	v_cndmask_b32_e64 v12, 0, 1, s[2:3]
	v_cmp_ne_u32_e32 vcc, 0, v12
	s_cmp_lg_u64 vcc, 0
	s_cselect_b64 s[2:3], -1, 0
	v_add_co_u32_e32 v11, vcc, -1, v11
	s_and_b64 s[2:3], s[2:3], vcc
	s_and_b64 vcc, exec, s[2:3]
	s_cbranch_vccnz .Lmy_sel_loop_5
	s_andn2_b64 s[2:3], exec, s[0:1]
	s_cbranch_scc0 .Lmy_sel_fast_5
	s_branch .Lmy_sel_slow

; __global__ void __launch_bounds__(512, 2) mega_fwd(KArgs a) {
;     ...
; #pragma unroll 1
;     ...
;                     const unsigned cand = tau | (1u << bit);
;                     int c0 = 0, c1 = 0;
; #pragma unroll
;                     for (int jj = 0; jj < 64; ++jj) { const unsigned long long bm = __ballot(key[jj] >= cand); c0 += __popc((unsigned)bm); c1 += __popc((unsigned)(bm >> 32)); }
;                     const int cnt = (lane < 32) ? c0 : c1;
;                     if (cnt >= 256) tau = cand;
;                     done_sel = done_sel || (cnt == 256);
;                     if (__ballot(!done_sel) == 0ull) break;
;                 }
.Lmy_sel_loop_4:
	v_lshl_or_b32 v12, 1, v11, v10
	v_add_u32_e32 v14, -1, v12
	v_mov_b32_e32 v13, 0
	v_med3_u32 v15, v3, v12, v14
	v_med3_u32 v16, v2, v12, v14
	v_add3_u32 v13, v13, v15, v16
	v_med3_u32 v15, v5, v12, v14
	v_med3_u32 v16, v4, v12, v14
	v_add3_u32 v13, v13, v15, v16
	v_med3_u32 v15, v7, v12, v14
	v_med3_u32 v16, v6, v12, v14
	v_add3_u32 v13, v13, v15, v16
	v_med3_u32 v15, v9, v12, v14
	v_med3_u32 v16, v8, v12, v14
	v_add3_u32 v13, v13, v15, v16
	v_med3_u32 v15, v102, v12, v14
	v_med3_u32 v16, v97, v12, v14
	v_add3_u32 v13, v13, v15, v16
	v_med3_u32 v15, v104, v12, v14
	v_med3_u32 v16, v99, v12, v14
	v_add3_u32 v13, v13, v15, v16
	v_med3_u32 v15, v106, v12, v14
	v_med3_u32 v16, v101, v12, v14
	v_add3_u32 v13, v13, v15, v16
	v_med3_u32 v15, v108, v12, v14
	v_med3_u32 v16, v103, v12, v14
	v_add3_u32 v13, v13, v15, v16
	v_med3_u32 v15, v110, v12, v14
	v_med3_u32 v16, v105, v12, v14
	v_add3_u32 v13, v13, v15, v16
	v_med3_u32 v15, v112, v12, v14
	v_med3_u32 v16, v107, v12, v14
	v_add3_u32 v13, v13, v15, v16
	v_med3_u32 v15, v114, v12, v14
	v_med3_u32 v16, v109, v12, v14
	v_add3_u32 v13, v13, v15, v16
	v_med3_u32 v15, v116, v12, v14
	v_med3_u32 v16, v111, v12, v14
	v_add3_u32 v13, v13, v15, v16
	v_med3_u32 v15, v118, v12, v14
	v_med3_u32 v16, v113, v12, v14
	v_add3_u32 v13, v13, v15, v16
	v_med3_u32 v15, v120, v12, v14
	v_med3_u32 v16, v115, v12, v14
	v_add3_u32 v13, v13, v15, v16
	v_med3_u32 v15, v122, v12, v14
	v_med3_u32 v16, v117, v12, v14
	v_add3_u32 v13, v13, v15, v16
	v_med3_u32 v15, v124, v12, v14
	v_med3_u32 v16, v119, v12, v14
	v_add3_u32 v13, v13, v15, v16
	v_mul_lo_u32 v15, v14, 32
	v_sub_u32_e32 v13, v13, v15
	s_nop 1
	v_add_u32_dpp v13, v13, v13 quad_perm:[1,0,3,2] row_mask:0xf bank_mask:0xf
	s_nop 1
	v_add_u32_dpp v13, v13, v13 quad_perm:[2,3,0,1] row_mask:0xf bank_mask:0xf
	s_nop 1
	v_add_u32_dpp v13, v13, v13 row_half_mirror row_mask:0xf bank_mask:0xf
	s_nop 1
	v_add_u32_dpp v13, v13, v13 row_mirror row_mask:0xf bank_mask:0xf
	v_mov_b32_e32 v14, v13
	s_nop 1
	v_permlane16_swap_b32 v14, v13
	v_add_u32_e32 v13, v13, v14
	s_movk_i32 s2, 0xff
	v_cmp_lt_i32_e32 vcc, s2, v13
	s_nop 1
	v_cndmask_b32_e32 v10, v10, v12, vcc
	v_cmp_eq_u32_e32 vcc, s5, v13
	s_or_b64 s[0:1], s[0:1], vcc
	s_xor_b64 s[2:3], s[0:1], -1
	v_cndmask_b32_e64 v12, 0, 1, s[2:3]
	v_cmp_ne_u32_e32 vcc, 0, v12
	s_cmp_lg_u64 vcc, 0
	s_cselect_b64 s[2:3], -1, 0
	v_add_co_u32_e32 v11, vcc, -1, v11
	s_and_b64 s[2:3], s[2:3], vcc
	s_and_b64 vcc, exec, s[2:3]
	s_cbranch_vccnz .Lmy_sel_loop_4
	s_andn2_b64 s[2:3], exec, s[0:1]
	s_cbranch_scc0 .Lmy_sel_fast_4
	s_branch .Lmy_sel_slow

; __global__ void __launch_bounds__(512, 2) mega_fwd(KArgs a) {
;     ...
; #pragma unroll 1
;     ...
;                     const unsigned cand = tau | (1u << bit);
;                     int c0 = 0, c1 = 0;
; #pragma unroll
;                     for (int jj = 0; jj < 64; ++jj) { const unsigned long long bm = __ballot(key[jj] >= cand); c0 += __popc((unsigned)bm); c1 += __popc((unsigned)(bm >> 32)); }
;                     const int cnt = (lane < 32) ? c0 : c1;
;                     if (cnt >= 256) tau = cand;
;                     done_sel = done_sel || (cnt == 256);
;                     if (__ballot(!done_sel) == 0ull) break;
;                 }
.Lmy_sel_loop_3:
	v_lshl_or_b32 v12, 1, v11, v10
	v_add_u32_e32 v14, -1, v12
	v_mov_b32_e32 v13, 0
	v_med3_u32 v15, v3, v12, v14
	v_med3_u32 v16, v2, v12, v14
	v_add3_u32 v13, v13, v15, v16
	v_med3_u32 v15, v5, v12, v14
	v_med3_u32 v16, v4, v12, v14
	v_add3_u32 v13, v13, v15, v16
	v_med3_u32 v15, v7, v12, v14
	v_med3_u32 v16, v6, v12, v14
	v_add3_u32 v13, v13, v15, v16
	v_med3_u32 v15, v9, v12, v14
	v_med3_u32 v16, v8, v12, v14
	v_add3_u32 v13, v13, v15, v16
	v_med3_u32 v15, v102, v12, v14
	v_med3_u32 v16, v97, v12, v14
	v_add3_u32 v13, v13, v15, v16
	v_med3_u32 v15, v104, v12, v14
	v_med3_u32 v16, v99, v12, v14
	v_add3_u32 v13, v13, v15, v16
	v_med3_u32 v15, v106, v12, v14
	v_med3_u32 v16, v101, v12, v14
	v_add3_u32 v13, v13, v15, v16
	v_med3_u32 v15, v108, v12, v14
	v_med3_u32 v16, v103, v12, v14
	v_add3_u32 v13, v13, v15, v16
	v_med3_u32 v15, v110, v12, v14
	v_med3_u32 v16, v105, v12, v14
	v_add3_u32 v13, v13, v15, v16
	v_med3_u32 v15, v112, v12, v14
	v_med3_u32 v16, v107, v12, v14
	v_add3_u32 v13, v13, v15, v16
	v_med3_u32 v15, v114, v12, v14
	v_med3_u32 v16, v109, v12, v14
	v_add3_u32 v13, v13, v15, v16
	v_med3_u32 v15, v116, v12, v14
	v_med3_u32 v16, v111, v12, v14
	v_add3_u32 v13, v13, v15, v16
	v_mul_lo_u32 v15, v14, 24
	v_sub_u32_e32 v13, v13, v15
	s_nop 1
	v_add_u32_dpp v13, v13, v13 quad_perm:[1,0,3,2] row_mask:0xf bank_mask:0xf
	s_nop 1
	v_add_u32_dpp v13, v13, v13 quad_perm:[2,3,0,1] row_mask:0xf bank_mask:0xf
	s_nop 1
	v_add_u32_dpp v13, v13, v13 row_half_mirror row_mask:0xf bank_mask:0xf
	s_nop 1
	v_add_u32_dpp v13, v13, v13 row_mirror row_mask:0xf bank_mask:0xf
	v_mov_b32_e32 v14, v13
	s_nop 1
	v_permlane16_swap_b32 v14, v13
	v_add_u32_e32 v13, v13, v14
	s_movk_i32 s2, 0xff
	v_cmp_lt_i32_e32 vcc, s2, v13
	s_nop 1
	v_cndmask_b32_e32 v10, v10, v12, vcc
	v_cmp_eq_u32_e32 vcc, s5, v13
	s_or_b64 s[0:1], s[0:1], vcc
	s_xor_b64 s[2:3], s[0:1], -1
	v_cndmask_b32_e64 v12, 0, 1, s[2:3]
	v_cmp_ne_u32_e32 vcc, 0, v12
	s_cmp_lg_u64 vcc, 0
	s_cselect_b64 s[2:3], -1, 0
	v_add_co_u32_e32 v11, vcc, -1, v11
	s_and_b64 s[2:3], s[2:3], vcc
	s_and_b64 vcc, exec, s[2:3]
	s_cbranch_vccnz .Lmy_sel_loop_3
	s_andn2_b64 s[2:3], exec, s[0:1]
	s_cbranch_scc0 .Lmy_sel_fast_3
	s_branch .Lmy_sel_slow

; __global__ void __launch_bounds__(512, 2) mega_fwd(KArgs a) {
;     ...
; #pragma unroll 1
;     ...
;                     const unsigned cand = tau | (1u << bit);
;                     int c0 = 0, c1 = 0;
; #pragma unroll
;                     for (int jj = 0; jj < 64; ++jj) { const unsigned long long bm = __ballot(key[jj] >= cand); c0 += __popc((unsigned)bm); c1 += __popc((unsigned)(bm >> 32)); }
;                     const int cnt = (lane < 32) ? c0 : c1;
;                     if (cnt >= 256) tau = cand;
;                     done_sel = done_sel || (cnt == 256);
;                     if (__ballot(!done_sel) == 0ull) break;
;                 }
.Lmy_sel_loop_2:
	v_lshl_or_b32 v12, 1, v11, v10
	v_add_u32_e32 v14, -1, v12
	v_mov_b32_e32 v13, 0
	v_med3_u32 v15, v3, v12, v14
	v_med3_u32 v16, v2, v12, v14
	v_add3_u32 v13, v13, v15, v16
	v_med3_u32 v15, v5, v12, v14
	v_med3_u32 v16, v4, v12, v14
	v_add3_u32 v13, v13, v15, v16
	v_med3_u32 v15, v7, v12, v14
	v_med3_u32 v16, v6, v12, v14
	v_add3_u32 v13, v13, v15, v16
	v_med3_u32 v15, v9, v12, v14
	v_med3_u32 v16, v8, v12, v14
	v_add3_u32 v13, v13, v15, v16
	v_med3_u32 v15, v102, v12, v14
	v_med3_u32 v16, v97, v12, v14
	v_add3_u32 v13, v13, v15, v16
	v_med3_u32 v15, v104, v12, v14
	v_med3_u32 v16, v99, v12, v14
	v_add3_u32 v13, v13, v15, v16
	v_med3_u32 v15, v106, v12, v14
	v_med3_u32 v16, v101, v12, v14
	v_add3_u32 v13, v13, v15, v16
	v_med3_u32 v15, v108, v12, v14
	v_med3_u32 v16, v103, v12, v14
	v_add3_u32 v13, v13, v15, v16
	v_mul_lo_u32 v15, v14, 16
	v_sub_u32_e32 v13, v13, v15
	s_nop 1
	v_add_u32_dpp v13, v13, v13 quad_perm:[1,0,3,2] row_mask:0xf bank_mask:0xf
	s_nop 1
	v_add_u32_dpp v13, v13, v13 quad_perm:[2,3,0,1] row_mask:0xf bank_mask:0xf
	s_nop 1
	v_add_u32_dpp v13, v13, v13 row_half_mirror row_mask:0xf bank_mask:0xf
	s_nop 1
	v_add_u32_dpp v13, v13, v13 row_mirror row_mask:0xf bank_mask:0xf
	v_mov_b32_e32 v14, v13
	s_nop 1
	v_permlane16_swap_b32 v14, v13
	v_add_u32_e32 v13, v13, v14
	s_movk_i32 s2, 0xff
	v_cmp_lt_i32_e32 vcc, s2, v13
	s_nop 1
	v_cndmask_b32_e32 v10, v10, v12, vcc
	v_cmp_eq_u32_e32 vcc, s5, v13
	s_or_b64 s[0:1], s[0:1], vcc
	s_xor_b64 s[2:3], s[0:1], -1
	v_cndmask_b32_e64 v12, 0, 1, s[2:3]
	v_cmp_ne_u32_e32 vcc, 0, v12
	s_cmp_lg_u64 vcc, 0
	s_cselect_b64 s[2:3], -1, 0
	v_add_co_u32_e32 v11, vcc, -1, v11
	s_and_b64 s[2:3], s[2:3], vcc
	s_and_b64 vcc, exec, s[2:3]
	s_cbranch_vccnz .Lmy_sel_loop_2
	s_andn2_b64 s[2:3], exec, s[0:1]
	s_cbranch_scc0 .Lmy_sel_fast_2
	s_branch .Lmy_sel_slow

; __global__ void __launch_bounds__(512, 2) mega_fwd(KArgs a) {
;     ...
; #pragma unroll 1
;     ...
;                     const unsigned cand = tau | (1u << bit);
;                     int c0 = 0, c1 = 0;
; #pragma unroll
;                     for (int jj = 0; jj < 64; ++jj) { const unsigned long long bm = __ballot(key[jj] >= cand); c0 += __popc((unsigned)bm); c1 += __popc((unsigned)(bm >> 32)); }
;                     const int cnt = (lane < 32) ? c0 : c1;
;                     if (cnt >= 256) tau = cand;
;                     done_sel = done_sel || (cnt == 256);
;                     if (__ballot(!done_sel) == 0ull) break;
;                 }
.Lmy_sel_loop_1:
	v_lshl_or_b32 v12, 1, v11, v10
	v_add_u32_e32 v14, -1, v12
	v_mov_b32_e32 v13, 0
	v_med3_u32 v15, v3, v12, v14
	v_med3_u32 v16, v2, v12, v14
	v_add3_u32 v13, v13, v15, v16
	v_med3_u32 v15, v5, v12, v14
	v_med3_u32 v16, v4, v12, v14
	v_add3_u32 v13, v13, v15, v16
	v_med3_u32 v15, v7, v12, v14
	v_med3_u32 v16, v6, v12, v14
	v_add3_u32 v13, v13, v15, v16
	v_med3_u32 v15, v9, v12, v14
	v_med3_u32 v16, v8, v12, v14
	v_add3_u32 v13, v13, v15, v16
	v_mul_lo_u32 v15, v14, 8
	v_sub_u32_e32 v13, v13, v15
	s_nop 1
	v_add_u32_dpp v13, v13, v13 quad_perm:[1,0,3,2] row_mask:0xf bank_mask:0xf
	s_nop 1
	v_add_u32_dpp v13, v13, v13 quad_perm:[2,3,0,1] row_mask:0xf bank_mask:0xf
	s_nop 1
	v_add_u32_dpp v13, v13, v13 row_half_mirror row_mask:0xf bank_mask:0xf
	s_nop 1
	v_add_u32_dpp v13, v13, v13 row_mirror row_mask:0xf bank_mask:0xf
	v_mov_b32_e32 v14, v13
	s_nop 1
	v_permlane16_swap_b32 v14, v13
	v_add_u32_e32 v13, v13, v14
	s_movk_i32 s2, 0xff
	v_cmp_lt_i32_e32 vcc, s2, v13
	s_nop 1
	v_cndmask_b32_e32 v10, v10, v12, vcc
	v_cmp_eq_u32_e32 vcc, s5, v13
	s_or_b64 s[0:1], s[0:1], vcc
	s_xor_b64 s[2:3], s[0:1], -1
	v_cndmask_b32_e64 v12, 0, 1, s[2:3]
	v_cmp_ne_u32_e32 vcc, 0, v12
	s_cmp_lg_u64 vcc, 0
	s_cselect_b64 s[2:3], -1, 0
	v_add_co_u32_e32 v11, vcc, -1, v11
	s_and_b64 s[2:3], s[2:3], vcc
	s_and_b64 vcc, exec, s[2:3]
	s_cbranch_vccnz .Lmy_sel_loop_1
	s_andn2_b64 s[2:3], exec, s[0:1]
	s_cbranch_scc0 .Lmy_sel_fast_1
	s_branch .Lmy_sel_slow
